# P7 final rmsnorm rewritten by hand: five items in flight (six rotating buffers), g_final loaded once
# baseline (speedup 1.0000x reference)
; __device__ __forceinline__ void phase7(const Params& p) {
;   const int tid = threadIdx.x;
;   float* X = p.out + OUT_Y;
;   const float* SSQ3 = (const float*)(p.ws + OFF_SSQ3);
;   for (int it = blockIdx.x; it < NT / 2; it += 2 * gridDim.x) {
;     const int it2 = it + (int)gridDim.x;
;     const bool has2 = it2 < NT / 2;
;     const size_t base = (size_t)it * 2048 + (size_t)tid * 8;
;     const size_t base2 = (size_t)(has2 ? it2 : it) * 2048 + (size_t)tid * 8;
;     const int row = (int)(base >> 10), k = (int)(base & 1023), row2 = (int)(base2 >> 10);
;     float4 a = *(const float4*)(X + base), b = *(const float4*)(X + base + 4);
;     float4 a2 = *(const float4*)(X + base2), b2 = *(const float4*)(X + base2 + 4);
;     const float rs = rsqrtf(SSQ3[row] * (1.f / 1024.f) + EPSF), rs2 = rsqrtf(SSQ3[row2] * (1.f / 1024.f) + EPSF);
;     float4 g0 = *(const float4*)(p.g_final + k), g1 = *(const float4*)(p.g_final + k + 4);
;     *(float4*)(X + base) = make_float4(a.x * rs * g0.x, a.y * rs * g0.y, a.z * rs * g0.z, a.w * rs * g0.w);
;     *(float4*)(X + base + 4) = make_float4(b.x * rs * g1.x, b.y * rs * g1.y, b.z * rs * g1.z, b.w * rs * g1.w);
;     if (has2) {
;       *(float4*)(X + base2) = make_float4(a2.x * rs2 * g0.x, a2.y * rs2 * g0.y, a2.z * rs2 * g0.z, a2.w * rs2 * g0.w);
;       *(float4*)(X + base2 + 4) = make_float4(b2.x * rs2 * g1.x, b2.y * rs2 * g1.y, b2.z * rs2 * g1.z, b2.w * rs2 * g1.w);
;     }
;   }
; }
.LBB0_1705:
	s_or_b64 exec, exec, s[0:1]
	s_cmpk_gt_i32 s96, 0x20ff
	s_waitcnt lgkmcnt(0)
	s_barrier
	s_cbranch_scc1 .LBB0_1710
	v_accvgpr_read_b32 v0, a140
	v_and_b32_e32 v2, 0xfe0, v0
	global_load_dwordx4 v[4:7], v2, s[76:77]
	global_load_dwordx4 v[100:103], v2, s[76:77] offset:16
	v_mov_b32_e32 v1, v0
	v_lshrrev_b32_e32 v11, 12, v0
	v_lshlrev_b32_e32 v11, 2, v11
	v_mov_b32_e32 v10, 0x358637bd
	s_mov_b32 s3, 0x800000
	s_mov_b32 s0, s96
	s_movk_i32 s13, 0x20ff
	s_mul_i32 s20, s82, 1
	s_mul_i32 s21, s82, 2
	s_mul_i32 s22, s82, 3
	s_mul_i32 s23, s82, 4
	s_mul_i32 s24, s82, 5
	s_mul_i32 s25, s82, 6
	s_mul_i32 s26, s82, 7
	s_mul_i32 s27, s82, 8
	s_mul_i32 s28, s82, 9
	s_mul_i32 s29, s82, 10
	s_mul_i32 s30, s82, 11
	s_min_u32 s12, s0, s13
	s_lshl_b32 s11, s12, 13
	v_add_u32_e32 v12, s11, v1
	global_load_dwordx4 v[16:19], v12, s[78:79]
	global_load_dwordx4 v[20:23], v12, s[78:79] offset:16
	s_lshl_b32 s11, s12, 3
	v_add_u32_e32 v13, s11, v11
	global_load_dword v24, v13, s[92:93]
	global_load_dword v96, v13, s[92:93]
	global_load_dword v96, v13, s[92:93]
	s_add_u32 s12, s0, s20
	s_min_u32 s12, s12, s13
	s_lshl_b32 s11, s12, 13
	v_add_u32_e32 v12, s11, v1
	global_load_dwordx4 v[28:31], v12, s[78:79]
	global_load_dwordx4 v[32:35], v12, s[78:79] offset:16
	s_lshl_b32 s11, s12, 3
	v_add_u32_e32 v13, s11, v11
	global_load_dword v36, v13, s[92:93]
	global_load_dword v96, v13, s[92:93]
	global_load_dword v96, v13, s[92:93]
	s_add_u32 s12, s0, s21
	s_min_u32 s12, s12, s13
	s_lshl_b32 s11, s12, 13
	v_add_u32_e32 v12, s11, v1
	global_load_dwordx4 v[40:43], v12, s[78:79]
	global_load_dwordx4 v[44:47], v12, s[78:79] offset:16
	s_lshl_b32 s11, s12, 3
	v_add_u32_e32 v13, s11, v11
	global_load_dword v48, v13, s[92:93]
	global_load_dword v96, v13, s[92:93]
	global_load_dword v96, v13, s[92:93]
	s_add_u32 s12, s0, s22
	s_min_u32 s12, s12, s13
	s_lshl_b32 s11, s12, 13
	v_add_u32_e32 v12, s11, v1
	global_load_dwordx4 v[52:55], v12, s[78:79]
	global_load_dwordx4 v[56:59], v12, s[78:79] offset:16
	s_lshl_b32 s11, s12, 3
	v_add_u32_e32 v13, s11, v11
	global_load_dword v60, v13, s[92:93]
	global_load_dword v96, v13, s[92:93]
	global_load_dword v96, v13, s[92:93]
	s_add_u32 s12, s0, s23
	s_min_u32 s12, s12, s13
	s_lshl_b32 s11, s12, 13
	v_add_u32_e32 v12, s11, v1
	global_load_dwordx4 v[64:67], v12, s[78:79]
	global_load_dwordx4 v[68:71], v12, s[78:79] offset:16
	s_lshl_b32 s11, s12, 3
	v_add_u32_e32 v13, s11, v11
	global_load_dword v72, v13, s[92:93]
	global_load_dword v96, v13, s[92:93]
	global_load_dword v96, v13, s[92:93]
.Lp7_loop:
	s_add_u32 s12, s0, s24
	s_min_u32 s12, s12, s13
	s_lshl_b32 s11, s12, 13
	v_add_u32_e32 v12, s11, v1
	global_load_dwordx4 v[76:79], v12, s[78:79]
	global_load_dwordx4 v[80:83], v12, s[78:79] offset:16
	s_lshl_b32 s11, s12, 3
	v_add_u32_e32 v13, s11, v11
	global_load_dword v84, v13, s[92:93]
	s_waitcnt vmcnt(25)
	s_mov_b32 s14, s0
	s_cmp_lt_u32 s14, 0x2100
	s_cbranch_scc0 .Lp7_done
	v_fmamk_f32 v14, v24, 0x3a800000, v10
	v_mul_f32_e32 v15, 0x4b800000, v14
	v_cmp_gt_f32_e32 vcc, s3, v14
	s_nop 1
	v_cndmask_b32_e32 v14, v14, v15, vcc
	v_rsq_f32_e32 v14, v14
	s_nop 0
	v_mul_f32_e32 v15, 0x45800000, v14
	v_cndmask_b32_e32 v14, v14, v15, vcc
	v_pk_mul_f32 v[88:89], v[16:17], v[14:15] op_sel_hi:[1,0]
	v_pk_mul_f32 v[90:91], v[18:19], v[14:15] op_sel_hi:[1,0]
	v_pk_mul_f32 v[92:93], v[20:21], v[14:15] op_sel_hi:[1,0]
	v_pk_mul_f32 v[94:95], v[22:23], v[14:15] op_sel_hi:[1,0]
	v_pk_mul_f32 v[88:89], v[4:5], v[88:89]
	v_pk_mul_f32 v[90:91], v[6:7], v[90:91]
	v_pk_mul_f32 v[92:93], v[100:101], v[92:93]
	v_pk_mul_f32 v[94:95], v[102:103], v[94:95]
	s_lshl_b32 s11, s14, 13
	v_add_u32_e32 v12, s11, v1
	global_store_dwordx4 v12, v[88:91], s[78:79]
	global_store_dwordx4 v12, v[92:95], s[78:79] offset:16
	s_add_u32 s12, s0, s25
	s_min_u32 s12, s12, s13
	s_lshl_b32 s11, s12, 13
	v_add_u32_e32 v12, s11, v1
	global_load_dwordx4 v[16:19], v12, s[78:79]
	global_load_dwordx4 v[20:23], v12, s[78:79] offset:16
	s_lshl_b32 s11, s12, 3
	v_add_u32_e32 v13, s11, v11
	global_load_dword v24, v13, s[92:93]
	s_waitcnt vmcnt(25)
	s_add_u32 s14, s0, s20
	s_cmp_lt_u32 s14, 0x2100
	s_cbranch_scc0 .Lp7_done
	v_fmamk_f32 v14, v36, 0x3a800000, v10
	v_mul_f32_e32 v15, 0x4b800000, v14
	v_cmp_gt_f32_e32 vcc, s3, v14
	s_nop 1
	v_cndmask_b32_e32 v14, v14, v15, vcc
	v_rsq_f32_e32 v14, v14
	s_nop 0
	v_mul_f32_e32 v15, 0x45800000, v14
	v_cndmask_b32_e32 v14, v14, v15, vcc
	v_pk_mul_f32 v[88:89], v[28:29], v[14:15] op_sel_hi:[1,0]
	v_pk_mul_f32 v[90:91], v[30:31], v[14:15] op_sel_hi:[1,0]
	v_pk_mul_f32 v[92:93], v[32:33], v[14:15] op_sel_hi:[1,0]
	v_pk_mul_f32 v[94:95], v[34:35], v[14:15] op_sel_hi:[1,0]
	v_pk_mul_f32 v[88:89], v[4:5], v[88:89]
	v_pk_mul_f32 v[90:91], v[6:7], v[90:91]
	v_pk_mul_f32 v[92:93], v[100:101], v[92:93]
	v_pk_mul_f32 v[94:95], v[102:103], v[94:95]
	s_lshl_b32 s11, s14, 13
	v_add_u32_e32 v12, s11, v1
	global_store_dwordx4 v12, v[88:91], s[78:79]
	global_store_dwordx4 v12, v[92:95], s[78:79] offset:16
	s_add_u32 s12, s0, s26
	s_min_u32 s12, s12, s13
	s_lshl_b32 s11, s12, 13
	v_add_u32_e32 v12, s11, v1
	global_load_dwordx4 v[28:31], v12, s[78:79]
	global_load_dwordx4 v[32:35], v12, s[78:79] offset:16
	s_lshl_b32 s11, s12, 3
	v_add_u32_e32 v13, s11, v11
	global_load_dword v36, v13, s[92:93]
	s_waitcnt vmcnt(25)
	s_add_u32 s14, s0, s21
	s_cmp_lt_u32 s14, 0x2100
	s_cbranch_scc0 .Lp7_done
; __device__ __forceinline__ void phase7(const Params& p) {
;   const int tid = threadIdx.x;
;   float* X = p.out + OUT_Y;
;   const float* SSQ3 = (const float*)(p.ws + OFF_SSQ3);
;   for (int it = blockIdx.x; it < NT / 2; it += 2 * gridDim.x) {
;     const int it2 = it + (int)gridDim.x;
;     const bool has2 = it2 < NT / 2;
;     const size_t base = (size_t)it * 2048 + (size_t)tid * 8;
;     const size_t base2 = (size_t)(has2 ? it2 : it) * 2048 + (size_t)tid * 8;
;     const int row = (int)(base >> 10), k = (int)(base & 1023), row2 = (int)(base2 >> 10);
;     float4 a = *(const float4*)(X + base), b = *(const float4*)(X + base + 4);
;     float4 a2 = *(const float4*)(X + base2), b2 = *(const float4*)(X + base2 + 4);
;     const float rs = rsqrtf(SSQ3[row] * (1.f / 1024.f) + EPSF), rs2 = rsqrtf(SSQ3[row2] * (1.f / 1024.f) + EPSF);
;     float4 g0 = *(const float4*)(p.g_final + k), g1 = *(const float4*)(p.g_final + k + 4);
;     *(float4*)(X + base) = make_float4(a.x * rs * g0.x, a.y * rs * g0.y, a.z * rs * g0.z, a.w * rs * g0.w);
;     *(float4*)(X + base + 4) = make_float4(b.x * rs * g1.x, b.y * rs * g1.y, b.z * rs * g1.z, b.w * rs * g1.w);
;     if (has2) {
;       *(float4*)(X + base2) = make_float4(a2.x * rs2 * g0.x, a2.y * rs2 * g0.y, a2.z * rs2 * g0.z, a2.w * rs2 * g0.w);
;       *(float4*)(X + base2 + 4) = make_float4(b2.x * rs2 * g1.x, b2.y * rs2 * g1.y, b2.z * rs2 * g1.z, b2.w * rs2 * g1.w);
;     }
;   }
; }
	v_fmamk_f32 v14, v48, 0x3a800000, v10
	v_mul_f32_e32 v15, 0x4b800000, v14
	v_cmp_gt_f32_e32 vcc, s3, v14
	s_nop 1
	v_cndmask_b32_e32 v14, v14, v15, vcc
	v_rsq_f32_e32 v14, v14
	s_nop 0
	v_mul_f32_e32 v15, 0x45800000, v14
	v_cndmask_b32_e32 v14, v14, v15, vcc
	v_pk_mul_f32 v[88:89], v[40:41], v[14:15] op_sel_hi:[1,0]
	v_pk_mul_f32 v[90:91], v[42:43], v[14:15] op_sel_hi:[1,0]
	v_pk_mul_f32 v[92:93], v[44:45], v[14:15] op_sel_hi:[1,0]
	v_pk_mul_f32 v[94:95], v[46:47], v[14:15] op_sel_hi:[1,0]
	v_pk_mul_f32 v[88:89], v[4:5], v[88:89]
	v_pk_mul_f32 v[90:91], v[6:7], v[90:91]
	v_pk_mul_f32 v[92:93], v[100:101], v[92:93]
	v_pk_mul_f32 v[94:95], v[102:103], v[94:95]
	s_lshl_b32 s11, s14, 13
	v_add_u32_e32 v12, s11, v1
	global_store_dwordx4 v12, v[88:91], s[78:79]
	global_store_dwordx4 v12, v[92:95], s[78:79] offset:16
	s_add_u32 s12, s0, s27
	s_min_u32 s12, s12, s13
	s_lshl_b32 s11, s12, 13
	v_add_u32_e32 v12, s11, v1
	global_load_dwordx4 v[40:43], v12, s[78:79]
	global_load_dwordx4 v[44:47], v12, s[78:79] offset:16
	s_lshl_b32 s11, s12, 3
	v_add_u32_e32 v13, s11, v11
	global_load_dword v48, v13, s[92:93]
	s_waitcnt vmcnt(25)
	s_add_u32 s14, s0, s22
	s_cmp_lt_u32 s14, 0x2100
	s_cbranch_scc0 .Lp7_done
	v_fmamk_f32 v14, v60, 0x3a800000, v10
	v_mul_f32_e32 v15, 0x4b800000, v14
	v_cmp_gt_f32_e32 vcc, s3, v14
	s_nop 1
	v_cndmask_b32_e32 v14, v14, v15, vcc
	v_rsq_f32_e32 v14, v14
	s_nop 0
	v_mul_f32_e32 v15, 0x45800000, v14
	v_cndmask_b32_e32 v14, v14, v15, vcc
	v_pk_mul_f32 v[88:89], v[52:53], v[14:15] op_sel_hi:[1,0]
	v_pk_mul_f32 v[90:91], v[54:55], v[14:15] op_sel_hi:[1,0]
	v_pk_mul_f32 v[92:93], v[56:57], v[14:15] op_sel_hi:[1,0]
	v_pk_mul_f32 v[94:95], v[58:59], v[14:15] op_sel_hi:[1,0]
	v_pk_mul_f32 v[88:89], v[4:5], v[88:89]
	v_pk_mul_f32 v[90:91], v[6:7], v[90:91]
	v_pk_mul_f32 v[92:93], v[100:101], v[92:93]
	v_pk_mul_f32 v[94:95], v[102:103], v[94:95]
	s_lshl_b32 s11, s14, 13
	v_add_u32_e32 v12, s11, v1
	global_store_dwordx4 v12, v[88:91], s[78:79]
	global_store_dwordx4 v12, v[92:95], s[78:79] offset:16
	s_add_u32 s12, s0, s28
	s_min_u32 s12, s12, s13
	s_lshl_b32 s11, s12, 13
	v_add_u32_e32 v12, s11, v1
	global_load_dwordx4 v[52:55], v12, s[78:79]
	global_load_dwordx4 v[56:59], v12, s[78:79] offset:16
	s_lshl_b32 s11, s12, 3
	v_add_u32_e32 v13, s11, v11
	global_load_dword v60, v13, s[92:93]
	s_waitcnt vmcnt(25)
	s_add_u32 s14, s0, s23
	s_cmp_lt_u32 s14, 0x2100
	s_cbranch_scc0 .Lp7_done
	v_fmamk_f32 v14, v72, 0x3a800000, v10
	v_mul_f32_e32 v15, 0x4b800000, v14
	v_cmp_gt_f32_e32 vcc, s3, v14
	s_nop 1
	v_cndmask_b32_e32 v14, v14, v15, vcc
	v_rsq_f32_e32 v14, v14
	s_nop 0
	v_mul_f32_e32 v15, 0x45800000, v14
	v_cndmask_b32_e32 v14, v14, v15, vcc
	v_pk_mul_f32 v[88:89], v[64:65], v[14:15] op_sel_hi:[1,0]
	v_pk_mul_f32 v[90:91], v[66:67], v[14:15] op_sel_hi:[1,0]
	v_pk_mul_f32 v[92:93], v[68:69], v[14:15] op_sel_hi:[1,0]
	v_pk_mul_f32 v[94:95], v[70:71], v[14:15] op_sel_hi:[1,0]
	v_pk_mul_f32 v[88:89], v[4:5], v[88:89]
	v_pk_mul_f32 v[90:91], v[6:7], v[90:91]
	v_pk_mul_f32 v[92:93], v[100:101], v[92:93]
	v_pk_mul_f32 v[94:95], v[102:103], v[94:95]
	s_lshl_b32 s11, s14, 13
	v_add_u32_e32 v12, s11, v1
	global_store_dwordx4 v12, v[88:91], s[78:79]
	global_store_dwordx4 v12, v[92:95], s[78:79] offset:16
	s_add_u32 s12, s0, s29
	s_min_u32 s12, s12, s13
	s_lshl_b32 s11, s12, 13
	v_add_u32_e32 v12, s11, v1
	global_load_dwordx4 v[64:67], v12, s[78:79]
	global_load_dwordx4 v[68:71], v12, s[78:79] offset:16
	s_lshl_b32 s11, s12, 3
	v_add_u32_e32 v13, s11, v11
	global_load_dword v72, v13, s[92:93]
	s_waitcnt vmcnt(25)
	s_add_u32 s14, s0, s24
	s_cmp_lt_u32 s14, 0x2100
	s_cbranch_scc0 .Lp7_done
	v_fmamk_f32 v14, v84, 0x3a800000, v10
	v_mul_f32_e32 v15, 0x4b800000, v14
	v_cmp_gt_f32_e32 vcc, s3, v14
	s_nop 1
	v_cndmask_b32_e32 v14, v14, v15, vcc
	v_rsq_f32_e32 v14, v14
	s_nop 0
	v_mul_f32_e32 v15, 0x45800000, v14
	v_cndmask_b32_e32 v14, v14, v15, vcc
	v_pk_mul_f32 v[88:89], v[76:77], v[14:15] op_sel_hi:[1,0]
	v_pk_mul_f32 v[90:91], v[78:79], v[14:15] op_sel_hi:[1,0]
	v_pk_mul_f32 v[92:93], v[80:81], v[14:15] op_sel_hi:[1,0]
	v_pk_mul_f32 v[94:95], v[82:83], v[14:15] op_sel_hi:[1,0]
	v_pk_mul_f32 v[88:89], v[4:5], v[88:89]
	v_pk_mul_f32 v[90:91], v[6:7], v[90:91]
	v_pk_mul_f32 v[92:93], v[100:101], v[92:93]
	v_pk_mul_f32 v[94:95], v[102:103], v[94:95]
	s_lshl_b32 s11, s14, 13
	v_add_u32_e32 v12, s11, v1
	global_store_dwordx4 v12, v[88:91], s[78:79]
	global_store_dwordx4 v12, v[92:95], s[78:79] offset:16
	s_add_u32 s0, s0, s25
	s_branch .Lp7_loop
.Lp7_done:
	s_waitcnt vmcnt(0)
.LBB0_1710:
	s_endpgm
